# seam2 counter + x-tile prefetch (global_load_dword touches) by waves 1-7 at SEAM5
# baseline (speedup 1.0000x reference)
; #define SEAM(k) do { if (IN(k) && IN((k) + 1)) xcd_barrier(bar); STAMP((k) + 1); } while (0)
; __device__ __forceinline__ void xcd_barrier(const XcdBarrier& b) {
;     asm volatile("s_waitcnt vmcnt(0)" ::: "memory");
;     __syncthreads();
;     if (threadIdx.x == 0) {
;         unsigned* bar = b.bar;
;         __builtin_amdgcn_s_waitcnt(0);
;         unsigned nloc = b.st[0], nx = b.st[1];
; __global__ void __launch_bounds__(512, 2) fwd_megakernel(Args a) {
;     ...
;     SEAM(5);
;     if (IN(6)) { pg8::Gemm g{(const u16*)(ws + Z_MERGED), (const u16*)(ws + WS_WO), TT, 1024, 1024}; pg8::StaticOrder S; S.init(TT, 1024, G, bx);
;         EpiOutNorm E{P.x, P.out, P.fnw, (float*)(ws + WS_BAR + 65536), (unsigned*)(ws + WS_BAR + 16384)}; pg8::gemm_phase<EpiOutNorm, pg8::StaticOrder, false, true>(lds, g, S, E); }
.LBB0_611:
	s_cmp_gt_i32 s83, 6
	s_cselect_b64 s[0:1], -1, 0
	s_and_b64 s[4:5], s[4:5], s[0:1]
	s_andn2_b64 vcc, exec, s[4:5]
	s_cbranch_vccnz .LBB0_665
	s_waitcnt vmcnt(0)
	s_waitcnt vmcnt(0) lgkmcnt(0)
	s_barrier
	v_readfirstlane_b32 s98, v188
	s_nop 3
	s_cmp_lt_u32 s98, 64
	s_cbranch_scc1 .Lxpf_skip
	s_and_b32 s98, s2, 7
	s_lshl_b32 s98, s98, 3
	s_bfe_u32 s99, s2, 0x30003
	s_add_u32 s98, s98, s99
	s_lshr_b32 s99, s2, 6
	s_lshl_b32 s98, s98, 20
	s_lshl_b32 s99, s99, 10
	s_add_u32 s98, s98, s99
	v_subrev_u32_e32 v230, 64, v188
	v_mov_b32_e32 v231, v230
	v_min_u32_e32 v231, 0x7ff, v231
	v_lshrrev_b32_e32 v232, 3, v231
	v_and_b32_e32 v233, 7, v231
	v_lshlrev_b32_e32 v232, 12, v232
	v_lshl_add_u32 v232, v233, 7, v232
	v_add_u32_e32 v232, s98, v232
	global_load_dword v236, v232, s[56:57]
	v_add_u32_e32 v231, 448, v230
	v_min_u32_e32 v231, 0x7ff, v231
	v_lshrrev_b32_e32 v232, 3, v231
	v_and_b32_e32 v233, 7, v231
	v_lshlrev_b32_e32 v232, 12, v232
	v_lshl_add_u32 v232, v233, 7, v232
	v_add_u32_e32 v232, s98, v232
	global_load_dword v237, v232, s[56:57]
	v_add_u32_e32 v231, 896, v230
	v_min_u32_e32 v231, 0x7ff, v231
	v_lshrrev_b32_e32 v232, 3, v231
	v_and_b32_e32 v233, 7, v231
	v_lshlrev_b32_e32 v232, 12, v232
	v_lshl_add_u32 v232, v233, 7, v232
	v_add_u32_e32 v232, s98, v232
	global_load_dword v238, v232, s[56:57]
	v_add_u32_e32 v231, 1344, v230
	v_min_u32_e32 v231, 0x7ff, v231
	v_lshrrev_b32_e32 v232, 3, v231
	v_and_b32_e32 v233, 7, v231
	v_lshlrev_b32_e32 v232, 12, v232
	v_lshl_add_u32 v232, v233, 7, v232
	v_add_u32_e32 v232, s98, v232
	global_load_dword v239, v232, s[56:57]
	v_add_u32_e32 v231, 1792, v230
	v_min_u32_e32 v231, 0x7ff, v231
	v_lshrrev_b32_e32 v232, 3, v231
	v_and_b32_e32 v233, 7, v231
	v_lshlrev_b32_e32 v232, 12, v232
	v_lshl_add_u32 v232, v233, 7, v232
	v_add_u32_e32 v232, s98, v232
	global_load_dword v240, v232, s[56:57]
.Lxpf_skip:
	s_mov_b64 s[4:5], exec
	v_readlane_b32 s6, v248, 2
	v_readlane_b32 s7, v248, 3
	s_and_b64 s[6:7], s[4:5], s[6:7]
	s_mov_b64 exec, s[6:7]
	s_cbranch_execz .LBB0_664
	s_add_i32 s6, 0, 0x27e00
	v_mov_b32_e32 v0, s6
	s_waitcnt vmcnt(0) expcnt(0) lgkmcnt(0)
	ds_read_b32 v2, v0
	s_add_i32 s6, 0, 0x27e04
	v_mov_b32_e32 v0, s6
	ds_read_b32 v0, v0
	s_waitcnt lgkmcnt(1)
	v_cmp_ne_u32_e32 vcc, 0, v2
	s_cbranch_vccnz .LBB0_628
	s_add_u32 s6, s78, 0x1f00200
	s_addc_u32 s7, s79, 0
	s_add_u32 s8, s78, 0x1f00400
	s_addc_u32 s9, s79, 0
	s_add_u32 s10, s78, 0x1f00500
	s_addc_u32 s11, s79, 0
	s_add_u32 s12, s78, 0x1f00600
	s_addc_u32 s13, s79, 0
	s_add_u32 s14, s78, 0x1f00700
	s_addc_u32 s15, s79, 0
	s_add_u32 s16, s78, 0x1f00800
	s_addc_u32 s17, s79, 0
	s_add_u32 s18, s78, 0x1f00900
	s_addc_u32 s19, s79, 0
	s_add_u32 s20, s78, 0x1f00a00
	s_addc_u32 s21, s79, 0
	s_add_u32 s22, s78, 0x1f00b00
	s_addc_u32 s23, s79, 0
	s_add_u32 s24, s78, 0x1f00c00
	s_addc_u32 s25, s79, 0
	s_add_u32 s26, s78, 0x1f00d00
	s_addc_u32 s27, s79, 0
	s_add_u32 s28, s78, 0x1f00e00
	s_addc_u32 s29, s79, 0
	s_add_u32 s30, s78, 0x1f00f00
	s_addc_u32 s31, s79, 0
	s_add_u32 s34, s78, 0x1f01000
	s_addc_u32 s35, s79, 0
	s_add_u32 s36, s78, 0x1f01100
	s_addc_u32 s37, s79, 0
	s_add_u32 s38, s78, 0x1f01200
	s_addc_u32 s39, s79, 0
	s_mul_i32 s33, s81, s33
	s_add_u32 s40, s78, 0x1f01300
	s_mul_i32 s33, s33, s80
	s_addc_u32 s41, s79, 0
	s_mov_b32 s48, 1
	v_mov_b32_e32 v16, 0
	s_branch .LBB0_616
